# scan2 carry chain rewritten on f32 MFMA (v_mfma_f32_16x16x4_f32), 1 barrier/chunk, 3-chunk prefetch
# speedup vs baseline: 1.1054x; 1.0014x over previous
.LBB0_726:
	s_add_u32 s2, s54, 0x4000000
	s_addc_u32 s3, s55, 0
	s_andn2_b64 vcc, exec, s[6:7]
	s_cbranch_vccnz .LBB0_735
	v_mov_b32_e32 v151, 0
	v_and_b32_e32 v108, 15, v196
	v_bfe_u32 v109, v196, 4, 2
	v_lshrrev_b32_e32 v110, 6, v196
	v_lshlrev_b32_e32 v111, 6, v110
	v_lshl_add_u32 v104, v109, 12, v111
	v_lshl_add_u32 v104, v108, 2, v104
	v_lshl_add_u32 v105, v108, 8, v111
	v_lshl_add_u32 v105, v109, 4, v105
	v_mul_u32_u24_e32 v106, 0x110, v108
	v_add_u32_e32 v107, v106, v111
	v_lshl_add_u32 v107, v109, 4, v107
	v_add_u32_e32 v107, 16, v107
	v_lshl_add_u32 v106, v109, 6, v106
	v_add_u32_e32 v106, 16, v106
	v_mov_b32_e32 v112, 0
	v_mov_b32_e32 v113, 0
	v_mov_b32_e32 v114, 0
	v_mov_b32_e32 v115, 0
	s_mov_b32 s10, s12
.Lsc2_unit:
	s_andn2_b32 s0, s10, 3
	s_lshl_b32 s0, s0, 17
	s_and_b32 s1, s10, 3
	s_lshl_b32 s1, s1, 12
	s_add_u32 s4, s2, s0
	s_addc_u32 s5, s3, 0
	s_add_u32 s4, s4, s1
	s_addc_u32 s5, s5, 0
	s_sub_u32 vcc_lo, 0x2000000, s1
	s_mov_b64 s[8:9], s[4:5]
	s_barrier
	s_add_u32 s6, s4, 0x0
	s_addc_u32 s7, s5, 0
	global_load_dwordx4 v[16:19], v105, s[6:7]
	s_add_u32 s6, s6, vcc_lo
	s_addc_u32 s7, s7, 0
	global_load_dword v0, v104, s[6:7]
	global_load_dword v1, v104, s[6:7] offset:256
	global_load_dword v2, v104, s[6:7] offset:512
	global_load_dword v3, v104, s[6:7] offset:768
	global_load_dword v4, v104, s[6:7] offset:1024
	global_load_dword v5, v104, s[6:7] offset:1280
	global_load_dword v6, v104, s[6:7] offset:1536
	global_load_dword v7, v104, s[6:7] offset:1792
	global_load_dword v8, v104, s[6:7] offset:2048
	global_load_dword v9, v104, s[6:7] offset:2304
	global_load_dword v10, v104, s[6:7] offset:2560
	global_load_dword v11, v104, s[6:7] offset:2816
	global_load_dword v12, v104, s[6:7] offset:3072
	global_load_dword v13, v104, s[6:7] offset:3328
	global_load_dword v14, v104, s[6:7] offset:3584
	global_load_dword v15, v104, s[6:7] offset:3840
	s_add_u32 s6, s4, 0x4000
	s_addc_u32 s7, s5, 0
	global_load_dwordx4 v[36:39], v105, s[6:7]
	s_add_u32 s6, s6, vcc_lo
	s_addc_u32 s7, s7, 0
	global_load_dword v20, v104, s[6:7]
	global_load_dword v21, v104, s[6:7] offset:256
	global_load_dword v22, v104, s[6:7] offset:512
	global_load_dword v23, v104, s[6:7] offset:768
	global_load_dword v24, v104, s[6:7] offset:1024
	global_load_dword v25, v104, s[6:7] offset:1280
	global_load_dword v26, v104, s[6:7] offset:1536
	global_load_dword v27, v104, s[6:7] offset:1792
	global_load_dword v28, v104, s[6:7] offset:2048
	global_load_dword v29, v104, s[6:7] offset:2304
	global_load_dword v30, v104, s[6:7] offset:2560
	global_load_dword v31, v104, s[6:7] offset:2816
	global_load_dword v32, v104, s[6:7] offset:3072
	global_load_dword v33, v104, s[6:7] offset:3328
	global_load_dword v34, v104, s[6:7] offset:3584
	global_load_dword v35, v104, s[6:7] offset:3840
	s_add_u32 s6, s4, 0x8000
	s_addc_u32 s7, s5, 0
	global_load_dwordx4 v[56:59], v105, s[6:7]
	s_add_u32 s6, s6, vcc_lo
	s_addc_u32 s7, s7, 0
	global_load_dword v40, v104, s[6:7]
	global_load_dword v41, v104, s[6:7] offset:256
	global_load_dword v42, v104, s[6:7] offset:512
	global_load_dword v43, v104, s[6:7] offset:768
	global_load_dword v44, v104, s[6:7] offset:1024
	global_load_dword v45, v104, s[6:7] offset:1280
	global_load_dword v46, v104, s[6:7] offset:1536
	global_load_dword v47, v104, s[6:7] offset:1792
	global_load_dword v48, v104, s[6:7] offset:2048
	global_load_dword v49, v104, s[6:7] offset:2304
	global_load_dword v50, v104, s[6:7] offset:2560
	global_load_dword v51, v104, s[6:7] offset:2816
	global_load_dword v52, v104, s[6:7] offset:3072
	global_load_dword v53, v104, s[6:7] offset:3328
	global_load_dword v54, v104, s[6:7] offset:3584
	global_load_dword v55, v104, s[6:7] offset:3840
	ds_write_b128 v107, v[112:115] offset:4352
	s_mov_b32 s0, 0
	s_waitcnt lgkmcnt(0)
	s_barrier
.Lsc2_loop:
	s_add_u32 s1, s0, 3
	s_min_u32 s1, s1, 31
	s_lshl_b32 s1, s1, 14
	s_add_u32 s6, s4, s1
	s_addc_u32 s7, s5, 0
	global_load_dwordx4 v[76:79], v105, s[6:7]
	s_add_u32 s6, s6, vcc_lo
	s_addc_u32 s7, s7, 0
	global_load_dword v60, v104, s[6:7]
	global_load_dword v61, v104, s[6:7] offset:256
	global_load_dword v62, v104, s[6:7] offset:512
	global_load_dword v63, v104, s[6:7] offset:768
	global_load_dword v64, v104, s[6:7] offset:1024
	global_load_dword v65, v104, s[6:7] offset:1280
	global_load_dword v66, v104, s[6:7] offset:1536
	global_load_dword v67, v104, s[6:7] offset:1792
	global_load_dword v68, v104, s[6:7] offset:2048
	global_load_dword v69, v104, s[6:7] offset:2304
	global_load_dword v70, v104, s[6:7] offset:2560
	global_load_dword v71, v104, s[6:7] offset:2816
	global_load_dword v72, v104, s[6:7] offset:3072
	global_load_dword v73, v104, s[6:7] offset:3328
	global_load_dword v74, v104, s[6:7] offset:3584
	global_load_dword v75, v104, s[6:7] offset:3840
	ds_read_b128 v[80:83], v106 offset:4352
	ds_read_b128 v[84:87], v106 offset:4368
	ds_read_b128 v[88:91], v106 offset:4384
	ds_read_b128 v[92:95], v106 offset:4400
	s_waitcnt vmcnt(51)
	s_waitcnt lgkmcnt(0)
	v_mfma_f32_16x16x4_f32 v[16:19], v0, v80, v[16:19]
	v_mfma_f32_16x16x4_f32 v[96:99], v1, v81, 0
	v_mfma_f32_16x16x4_f32 v[16:19], v2, v82, v[16:19]
	v_mfma_f32_16x16x4_f32 v[96:99], v3, v83, v[96:99]
	v_mfma_f32_16x16x4_f32 v[16:19], v4, v84, v[16:19]
	v_mfma_f32_16x16x4_f32 v[96:99], v5, v85, v[96:99]
	v_mfma_f32_16x16x4_f32 v[16:19], v6, v86, v[16:19]
	v_mfma_f32_16x16x4_f32 v[96:99], v7, v87, v[96:99]
	v_mfma_f32_16x16x4_f32 v[16:19], v8, v88, v[16:19]
	v_mfma_f32_16x16x4_f32 v[96:99], v9, v89, v[96:99]
	v_mfma_f32_16x16x4_f32 v[16:19], v10, v90, v[16:19]
	v_mfma_f32_16x16x4_f32 v[96:99], v11, v91, v[96:99]
	v_mfma_f32_16x16x4_f32 v[16:19], v12, v92, v[16:19]
	v_mfma_f32_16x16x4_f32 v[96:99], v13, v93, v[96:99]
	v_mfma_f32_16x16x4_f32 v[16:19], v14, v94, v[16:19]
	v_mfma_f32_16x16x4_f32 v[96:99], v15, v95, v[96:99]
	s_add_i32 s0, s0, 1
	s_nop 7
	s_nop 7
	v_pk_add_f32 v[100:101], v[16:17], v[96:97]
	v_pk_add_f32 v[102:103], v[18:19], v[98:99]
	ds_write_b128 v107, v[100:103] offset:0
	global_store_dwordx4 v105, v[100:103], s[8:9]
	s_add_u32 s8, s8, 0x4000
	s_addc_u32 s9, s9, 0
	s_waitcnt lgkmcnt(0)
	s_barrier
	s_cmp_eq_u32 s0, 31
	s_cbranch_scc1 .Lsc2_done
	s_add_u32 s1, s0, 3
	s_min_u32 s1, s1, 31
	s_lshl_b32 s1, s1, 14
	s_add_u32 s6, s4, s1
	s_addc_u32 s7, s5, 0
	global_load_dwordx4 v[16:19], v105, s[6:7]
	s_add_u32 s6, s6, vcc_lo
	s_addc_u32 s7, s7, 0
	global_load_dword v0, v104, s[6:7]
	global_load_dword v1, v104, s[6:7] offset:256
	global_load_dword v2, v104, s[6:7] offset:512
	global_load_dword v3, v104, s[6:7] offset:768
	global_load_dword v4, v104, s[6:7] offset:1024
	global_load_dword v5, v104, s[6:7] offset:1280
	global_load_dword v6, v104, s[6:7] offset:1536
	global_load_dword v7, v104, s[6:7] offset:1792
	global_load_dword v8, v104, s[6:7] offset:2048
	global_load_dword v9, v104, s[6:7] offset:2304
	global_load_dword v10, v104, s[6:7] offset:2560
	global_load_dword v11, v104, s[6:7] offset:2816
	global_load_dword v12, v104, s[6:7] offset:3072
	global_load_dword v13, v104, s[6:7] offset:3328
	global_load_dword v14, v104, s[6:7] offset:3584
	global_load_dword v15, v104, s[6:7] offset:3840
	ds_read_b128 v[80:83], v106 offset:0
	ds_read_b128 v[84:87], v106 offset:16
	ds_read_b128 v[88:91], v106 offset:32
	ds_read_b128 v[92:95], v106 offset:48
	s_waitcnt vmcnt(51)
	s_waitcnt lgkmcnt(0)
	v_mfma_f32_16x16x4_f32 v[36:39], v20, v80, v[36:39]
	v_mfma_f32_16x16x4_f32 v[96:99], v21, v81, 0
	v_mfma_f32_16x16x4_f32 v[36:39], v22, v82, v[36:39]
	v_mfma_f32_16x16x4_f32 v[96:99], v23, v83, v[96:99]
	v_mfma_f32_16x16x4_f32 v[36:39], v24, v84, v[36:39]
	v_mfma_f32_16x16x4_f32 v[96:99], v25, v85, v[96:99]
	v_mfma_f32_16x16x4_f32 v[36:39], v26, v86, v[36:39]
	v_mfma_f32_16x16x4_f32 v[96:99], v27, v87, v[96:99]
	v_mfma_f32_16x16x4_f32 v[36:39], v28, v88, v[36:39]
	v_mfma_f32_16x16x4_f32 v[96:99], v29, v89, v[96:99]
	v_mfma_f32_16x16x4_f32 v[36:39], v30, v90, v[36:39]
	v_mfma_f32_16x16x4_f32 v[96:99], v31, v91, v[96:99]
	v_mfma_f32_16x16x4_f32 v[36:39], v32, v92, v[36:39]
	v_mfma_f32_16x16x4_f32 v[96:99], v33, v93, v[96:99]
	v_mfma_f32_16x16x4_f32 v[36:39], v34, v94, v[36:39]
	v_mfma_f32_16x16x4_f32 v[96:99], v35, v95, v[96:99]
	s_add_i32 s0, s0, 1
	s_nop 7
	s_nop 7
	v_pk_add_f32 v[100:101], v[36:37], v[96:97]
	v_pk_add_f32 v[102:103], v[38:39], v[98:99]
	ds_write_b128 v107, v[100:103] offset:4352
	global_store_dwordx4 v105, v[100:103], s[8:9]
	s_add_u32 s8, s8, 0x4000
	s_addc_u32 s9, s9, 0
	s_waitcnt lgkmcnt(0)
	s_barrier
	s_cmp_eq_u32 s0, 31
	s_cbranch_scc1 .Lsc2_done
	s_add_u32 s1, s0, 3
	s_min_u32 s1, s1, 31
	s_lshl_b32 s1, s1, 14
	s_add_u32 s6, s4, s1
	s_addc_u32 s7, s5, 0
	global_load_dwordx4 v[36:39], v105, s[6:7]
	s_add_u32 s6, s6, vcc_lo
	s_addc_u32 s7, s7, 0
	global_load_dword v20, v104, s[6:7]
	global_load_dword v21, v104, s[6:7] offset:256
	global_load_dword v22, v104, s[6:7] offset:512
	global_load_dword v23, v104, s[6:7] offset:768
	global_load_dword v24, v104, s[6:7] offset:1024
	global_load_dword v25, v104, s[6:7] offset:1280
	global_load_dword v26, v104, s[6:7] offset:1536
	global_load_dword v27, v104, s[6:7] offset:1792
	global_load_dword v28, v104, s[6:7] offset:2048
	global_load_dword v29, v104, s[6:7] offset:2304
	global_load_dword v30, v104, s[6:7] offset:2560
	global_load_dword v31, v104, s[6:7] offset:2816
	global_load_dword v32, v104, s[6:7] offset:3072
	global_load_dword v33, v104, s[6:7] offset:3328
	global_load_dword v34, v104, s[6:7] offset:3584
	global_load_dword v35, v104, s[6:7] offset:3840
	ds_read_b128 v[80:83], v106 offset:4352
	ds_read_b128 v[84:87], v106 offset:4368
	ds_read_b128 v[88:91], v106 offset:4384
	ds_read_b128 v[92:95], v106 offset:4400
	s_waitcnt vmcnt(51)
	s_waitcnt lgkmcnt(0)
	v_mfma_f32_16x16x4_f32 v[56:59], v40, v80, v[56:59]
	v_mfma_f32_16x16x4_f32 v[96:99], v41, v81, 0
	v_mfma_f32_16x16x4_f32 v[56:59], v42, v82, v[56:59]
	v_mfma_f32_16x16x4_f32 v[96:99], v43, v83, v[96:99]
	v_mfma_f32_16x16x4_f32 v[56:59], v44, v84, v[56:59]
	v_mfma_f32_16x16x4_f32 v[96:99], v45, v85, v[96:99]
	v_mfma_f32_16x16x4_f32 v[56:59], v46, v86, v[56:59]
	v_mfma_f32_16x16x4_f32 v[96:99], v47, v87, v[96:99]
	v_mfma_f32_16x16x4_f32 v[56:59], v48, v88, v[56:59]
	v_mfma_f32_16x16x4_f32 v[96:99], v49, v89, v[96:99]
	v_mfma_f32_16x16x4_f32 v[56:59], v50, v90, v[56:59]
	v_mfma_f32_16x16x4_f32 v[96:99], v51, v91, v[96:99]
	v_mfma_f32_16x16x4_f32 v[56:59], v52, v92, v[56:59]
	v_mfma_f32_16x16x4_f32 v[96:99], v53, v93, v[96:99]
	v_mfma_f32_16x16x4_f32 v[56:59], v54, v94, v[56:59]
	v_mfma_f32_16x16x4_f32 v[96:99], v55, v95, v[96:99]
	s_add_i32 s0, s0, 1
	s_nop 7
	s_nop 7
	v_pk_add_f32 v[100:101], v[56:57], v[96:97]
	v_pk_add_f32 v[102:103], v[58:59], v[98:99]
	ds_write_b128 v107, v[100:103] offset:0
	global_store_dwordx4 v105, v[100:103], s[8:9]
	s_add_u32 s8, s8, 0x4000
	s_addc_u32 s9, s9, 0
	s_waitcnt lgkmcnt(0)
	s_barrier
	s_cmp_eq_u32 s0, 31
	s_cbranch_scc1 .Lsc2_done
	s_add_u32 s1, s0, 3
	s_min_u32 s1, s1, 31
	s_lshl_b32 s1, s1, 14
	s_add_u32 s6, s4, s1
	s_addc_u32 s7, s5, 0
	global_load_dwordx4 v[56:59], v105, s[6:7]
	s_add_u32 s6, s6, vcc_lo
	s_addc_u32 s7, s7, 0
	global_load_dword v40, v104, s[6:7]
	global_load_dword v41, v104, s[6:7] offset:256
	global_load_dword v42, v104, s[6:7] offset:512
	global_load_dword v43, v104, s[6:7] offset:768
	global_load_dword v44, v104, s[6:7] offset:1024
	global_load_dword v45, v104, s[6:7] offset:1280
	global_load_dword v46, v104, s[6:7] offset:1536
	global_load_dword v47, v104, s[6:7] offset:1792
	global_load_dword v48, v104, s[6:7] offset:2048
	global_load_dword v49, v104, s[6:7] offset:2304
	global_load_dword v50, v104, s[6:7] offset:2560
	global_load_dword v51, v104, s[6:7] offset:2816
	global_load_dword v52, v104, s[6:7] offset:3072
	global_load_dword v53, v104, s[6:7] offset:3328
	global_load_dword v54, v104, s[6:7] offset:3584
	global_load_dword v55, v104, s[6:7] offset:3840
	ds_read_b128 v[80:83], v106 offset:0
	ds_read_b128 v[84:87], v106 offset:16
	ds_read_b128 v[88:91], v106 offset:32
	ds_read_b128 v[92:95], v106 offset:48
	s_waitcnt vmcnt(51)
	s_waitcnt lgkmcnt(0)
	v_mfma_f32_16x16x4_f32 v[76:79], v60, v80, v[76:79]
	v_mfma_f32_16x16x4_f32 v[96:99], v61, v81, 0
	v_mfma_f32_16x16x4_f32 v[76:79], v62, v82, v[76:79]
	v_mfma_f32_16x16x4_f32 v[96:99], v63, v83, v[96:99]
	v_mfma_f32_16x16x4_f32 v[76:79], v64, v84, v[76:79]
	v_mfma_f32_16x16x4_f32 v[96:99], v65, v85, v[96:99]
	v_mfma_f32_16x16x4_f32 v[76:79], v66, v86, v[76:79]
	v_mfma_f32_16x16x4_f32 v[96:99], v67, v87, v[96:99]
	v_mfma_f32_16x16x4_f32 v[76:79], v68, v88, v[76:79]
	v_mfma_f32_16x16x4_f32 v[96:99], v69, v89, v[96:99]
	v_mfma_f32_16x16x4_f32 v[76:79], v70, v90, v[76:79]
	v_mfma_f32_16x16x4_f32 v[96:99], v71, v91, v[96:99]
	v_mfma_f32_16x16x4_f32 v[76:79], v72, v92, v[76:79]
	v_mfma_f32_16x16x4_f32 v[96:99], v73, v93, v[96:99]
	v_mfma_f32_16x16x4_f32 v[76:79], v74, v94, v[76:79]
	v_mfma_f32_16x16x4_f32 v[96:99], v75, v95, v[96:99]
	s_add_i32 s0, s0, 1
	s_nop 7
	s_nop 7
	v_pk_add_f32 v[100:101], v[76:77], v[96:97]
	v_pk_add_f32 v[102:103], v[78:79], v[98:99]
	ds_write_b128 v107, v[100:103] offset:4352
	global_store_dwordx4 v105, v[100:103], s[8:9]
	s_add_u32 s8, s8, 0x4000
	s_addc_u32 s9, s9, 0
	s_waitcnt lgkmcnt(0)
	s_barrier
	s_cmp_eq_u32 s0, 31
	s_cbranch_scc0 .Lsc2_loop
.Lsc2_done:
	s_add_i32 s10, s10, s58
	s_cmpk_gt_i32 s10, 0xff
	s_cbranch_scc0 .Lsc2_unit
